# attention V phase: permlane nop slots filled with bookkeeping VALU / 2 cvts, alX=1.0 mov + resc v_cmp replaced by SALU flag, l kept in v150
# baseline (speedup 1.0000x reference)
; #define RESC(al) do { if (__any((al) < 1.f)) { if (hi == 0) al_l[r32] = (al); asm volatile("s_waitcnt lgkmcnt(0)" ::: "memory"); \
;         _Pragma("unroll") for (int d_ = 0; d_ < 2; ++d_) _Pragma("unroll") for (int r = 0; r < 16; ++r) o[d_][r] *= al_l[crow(r, hi)]; } } while (0)
; #define SHIFT(P0_, P1_, dl_) do { m_reg += (dl_); _Pragma("unroll") for (int r = 0; r < 16; ++r) { P0_[r] -= (dl_); P1_[r] -= (dl_); } _Pragma("unroll") for (int r = 0; r < 16; ++r) negm[r] = -m_reg; } while (0)
; template <int VAR> __device__ __forceinline__ void block(const bf16* Q, const bf16* KVB, const bf16* KR, const float* cosT, bf16* OB, LAS unsigned char* lds, int b, int h, int qb, int t0, int wv, ...
;     ...
;         float pm_, alX = 1.f; ROWMAX(px0, px1, pm_);
;         if (__builtin_expect(__any(pm_ > THR), 0)) { const float dl_ = fmaxf(pm_, 0.f); SHIFT(px0, px1, dl_); alX = __builtin_amdgcn_exp2f(-dl_); }
;         TILE_VALU(alX);
;         pa0 = pn0; pa1 = pn1; pa2 = pn2; pa3 = pn3;
;         RESC(alX);
;         sk = (sk + 1) & 3; sv = (sv + 1) & 3;
;     }
.LBB0_1417:
	v_max3_f32 v128, v48, v64, v49
	v_max3_f32 v129, v65, v50, v66
	v_max3_f32 v130, v51, v67, v52
	v_max3_f32 v131, v68, v53, v69
	v_max3_f32 v128, v128, v54, v70
	v_max3_f32 v129, v129, v55, v71
	v_max3_f32 v130, v130, v56, v72
	v_max3_f32 v131, v131, v57, v73
	v_max3_f32 v128, v128, v58, v74
	v_max3_f32 v129, v129, v59, v75
	v_max3_f32 v130, v130, v60, v76
	v_max3_f32 v131, v131, v61, v77
	v_max3_f32 v128, v128, v62, v78
	v_max3_f32 v129, v129, v63, v79
	v_max3_f32 v128, v128, v129, v130
	v_max_f32_e32 v128, v128, v131
	v_mov_b32_e32 v129, v128
	v_subrev_u32_e32 v173, 64, v173
	v_lshl_add_u64 v[154:155], v[154:155], 0, s[94:95]
	v_permlane32_swap_b32_e32 v128, v129
	v_max_f32_e32 v129, v128, v129
	s_mov_b32 s4, 0x41000000
	s_mov_b32 s5, 0
	v_cmp_lt_f32_e32 vcc, s4, v129
	v_lshl_add_u64 v[156:157], v[156:157], 0, s[70:71]
	v_lshl_add_u64 v[158:159], v[158:159], 0, s[94:95]
	s_cbranch_vccnz .LBB0_1429
.LBB0_1418:
	v_exp_f32_e32 v64, v64
	v_exp_f32_e32 v68, v68
	v_exp_f32_e32 v129, v48
	v_exp_f32_e32 v52, v52
	v_exp_f32_e32 v65, v65
	v_exp_f32_e32 v69, v69
	v_exp_f32_e32 v49, v49
	v_exp_f32_e32 v53, v53
	v_exp_f32_e32 v66, v66
	v_exp_f32_e32 v70, v70
	v_exp_f32_e32 v50, v50
	v_exp_f32_e32 v54, v54
	v_exp_f32_e32 v67, v67
	v_exp_f32_e32 v71, v71
	v_exp_f32_e32 v51, v51
	v_exp_f32_e32 v55, v55
	v_exp_f32_e32 v72, v72
	v_exp_f32_e32 v56, v56
	v_add_f32_e32 v48, v129, v64
	v_add_f32_e32 v133, v52, v68
	v_exp_f32_e32 v73, v73
	v_exp_f32_e32 v57, v57
	v_add_f32_e32 v130, v49, v65
	v_add_f32_e32 v48, v48, v133
	v_add_f32_e32 v133, v53, v69
	v_exp_f32_e32 v74, v74
	v_exp_f32_e32 v58, v58
	v_add_f32_e32 v131, v50, v66
	v_add_f32_e32 v130, v130, v133
	v_add_f32_e32 v133, v54, v70
	v_exp_f32_e32 v75, v75
	v_exp_f32_e32 v59, v59
	v_add_f32_e32 v132, v51, v67
	v_add_f32_e32 v131, v131, v133
	v_add_f32_e32 v133, v55, v71
	v_exp_f32_e32 v76, v76
	v_exp_f32_e32 v60, v60
	v_add_f32_e32 v132, v132, v133
	v_add_f32_e32 v133, v56, v72
	v_exp_f32_e32 v77, v77
	v_exp_f32_e32 v61, v61
	v_add_f32_e32 v48, v133, v48
	v_add_f32_e32 v133, v57, v73
	v_exp_f32_e32 v78, v78
	v_exp_f32_e32 v62, v62
	v_add_f32_e32 v130, v133, v130
	v_add_f32_e32 v133, v58, v74
	v_exp_f32_e32 v79, v79
	v_exp_f32_e32 v63, v63
	v_add_f32_e32 v131, v133, v131
	v_add_f32_e32 v133, v59, v75
	v_add_f32_e32 v132, v133, v132
	v_add_f32_e32 v133, v60, v76
	v_add_f32_e32 v48, v133, v48
	v_add_f32_e32 v133, v61, v77
	v_add_f32_e32 v130, v133, v130
	v_add_f32_e32 v133, v62, v78
	v_add_f32_e32 v131, v133, v131
	v_add_f32_e32 v133, v63, v79
	v_add_f32_e32 v132, v133, v132
	v_add_f32_e32 v48, v48, v130
	v_add_f32_e32 v130, v131, v132
	v_add_f32_e32 v48, v48, v130
	v_mov_b32_e32 v130, v48
	v_cvt_pk_bf16_f32 v140, v64, v65
	v_cvt_pk_bf16_f32 v141, v66, v67
	v_permlane32_swap_b32_e32 v48, v130
	s_cmp_lg_u32 s5, 0
	s_cbranch_scc1 .Lat_resc
	v_add_f32_e32 v48, v48, v130
	v_add_f32_e32 v150, v150, v48
.LBB0_1422:
	s_add_i32 s4, s82, 1
	s_and_b32 s82, s4, 3
	s_add_i32 s4, s68, 1
	s_add_i32 s85, s85, 1
	s_and_b32 s68, s4, 3
	s_add_i32 s4, s67, s85
	s_add_i32 s33, s33, 64
	v_cvt_pk_bf16_f32 v142, v68, v69
	v_cvt_pk_bf16_f32 v143, v70, v71
	v_cvt_pk_bf16_f32 v136, v72, v73
	v_cvt_pk_bf16_f32 v137, v74, v75
	v_cvt_pk_bf16_f32 v138, v76, v77
	v_cvt_pk_bf16_f32 v139, v78, v79
	v_cvt_pk_bf16_f32 v132, v129, v49
	v_cvt_pk_bf16_f32 v133, v50, v51
	v_cvt_pk_bf16_f32 v134, v52, v53
	v_cvt_pk_bf16_f32 v135, v54, v55
	v_cvt_pk_bf16_f32 v128, v56, v57
	v_cvt_pk_bf16_f32 v129, v58, v59
	v_cvt_pk_bf16_f32 v130, v60, v61
	v_cvt_pk_bf16_f32 v131, v62, v63
	s_cmp_eq_u32 s4, 4
	s_cbranch_scc1 .LBB0_1430
	s_cmp_ge_u32 s85, s66
	s_cselect_b64 s[4:5], -1, 0
	s_cbranch_scc1 .Lat_mbar0
	s_waitcnt vmcnt(6) lgkmcnt(0)
	s_barrier
	s_branch .Lat_mreads

.Lat_resc:
	v_add_f32_e32 v48, v48, v130
	v_fma_f32 v150, v150, v128, v48
	s_and_saveexec_b64 s[4:5], s[2:3]
	ds_write_b32 v171, v128 offset:128
	s_or_b64 exec, exec, s[4:5]
	s_waitcnt lgkmcnt(0)
	ds_read_b128 v[80:83], v168 offset:224
	ds_read_b128 v[84:87], v168 offset:192
	ds_read_b128 v[88:91], v168 offset:160
	ds_read_b128 v[92:95], v168 offset:128
	s_waitcnt lgkmcnt(0)
	v_pk_mul_f32 v[30:31], v[30:31], v[82:83]
	v_pk_mul_f32 v[26:27], v[26:27], v[86:87]
	v_pk_mul_f32 v[22:23], v[22:23], v[90:91]
	v_pk_mul_f32 v[18:19], v[18:19], v[94:95]
	v_pk_mul_f32 v[28:29], v[28:29], v[80:81]
	v_pk_mul_f32 v[24:25], v[24:25], v[84:85]
	v_pk_mul_f32 v[20:21], v[20:21], v[88:89]
	v_pk_mul_f32 v[16:17], v[16:17], v[92:93]
	v_pk_mul_f32 v[14:15], v[14:15], v[82:83]
	v_pk_mul_f32 v[10:11], v[10:11], v[86:87]
	v_pk_mul_f32 v[6:7], v[6:7], v[90:91]
	v_pk_mul_f32 v[2:3], v[2:3], v[94:95]
	v_pk_mul_f32 v[12:13], v[12:13], v[80:81]
	v_pk_mul_f32 v[8:9], v[8:9], v[84:85]
	v_pk_mul_f32 v[4:5], v[4:5], v[88:89]
	v_pk_mul_f32 v[0:1], v[0:1], v[92:93]
	s_branch .LBB0_1422

; #define SHIFT(P0_, P1_, dl_) do { m_reg += (dl_); _Pragma("unroll") for (int r = 0; r < 16; ++r) { P0_[r] -= (dl_); P1_[r] -= (dl_); } _Pragma("unroll") for (int r = 0; r < 16; ++r) negm[r] = -m_reg; } while (0)
; template <int VAR> __device__ __forceinline__ void block(const bf16* Q, const bf16* KVB, const bf16* KR, const float* cosT, bf16* OB, LAS unsigned char* lds, int b, int h, int qb, int t0, int wv, ...
;     ...
;         if (__builtin_expect(__any(pm_ > THR), 0)) { const float dl_ = fmaxf(pm_, 0.f); SHIFT(px0, px1, dl_); alX = __builtin_amdgcn_exp2f(-dl_); }
.LBB0_1429:
	s_mov_b32 s5, 1
	v_max_f32_e32 v32, v129, v129
	v_max_f32_e32 v34, 0, v32
	v_exp_f32_e64 v128, -v34
	v_add_f32_e32 v151, v151, v34
	v_xor_b32_e32 v32, 0x80000000, v151
	v_pk_add_f32 v[64:65], v[64:65], v[34:35] op_sel_hi:[1,0] neg_lo:[0,1] neg_hi:[0,1]
	v_pk_add_f32 v[48:49], v[48:49], v[34:35] op_sel_hi:[1,0] neg_lo:[0,1] neg_hi:[0,1]
	v_pk_add_f32 v[66:67], v[66:67], v[34:35] op_sel_hi:[1,0] neg_lo:[0,1] neg_hi:[0,1]
	v_pk_add_f32 v[50:51], v[50:51], v[34:35] op_sel_hi:[1,0] neg_lo:[0,1] neg_hi:[0,1]
	v_pk_add_f32 v[68:69], v[68:69], v[34:35] op_sel_hi:[1,0] neg_lo:[0,1] neg_hi:[0,1]
	v_pk_add_f32 v[52:53], v[52:53], v[34:35] op_sel_hi:[1,0] neg_lo:[0,1] neg_hi:[0,1]
	v_pk_add_f32 v[70:71], v[70:71], v[34:35] op_sel_hi:[1,0] neg_lo:[0,1] neg_hi:[0,1]
	v_pk_add_f32 v[54:55], v[54:55], v[34:35] op_sel_hi:[1,0] neg_lo:[0,1] neg_hi:[0,1]
	v_pk_add_f32 v[72:73], v[72:73], v[34:35] op_sel_hi:[1,0] neg_lo:[0,1] neg_hi:[0,1]
	v_pk_add_f32 v[56:57], v[56:57], v[34:35] op_sel_hi:[1,0] neg_lo:[0,1] neg_hi:[0,1]
	v_pk_add_f32 v[74:75], v[74:75], v[34:35] op_sel_hi:[1,0] neg_lo:[0,1] neg_hi:[0,1]
	v_pk_add_f32 v[58:59], v[58:59], v[34:35] op_sel_hi:[1,0] neg_lo:[0,1] neg_hi:[0,1]
	v_pk_add_f32 v[76:77], v[76:77], v[34:35] op_sel_hi:[1,0] neg_lo:[0,1] neg_hi:[0,1]
	v_pk_add_f32 v[60:61], v[60:61], v[34:35] op_sel_hi:[1,0] neg_lo:[0,1] neg_hi:[0,1]
	v_pk_add_f32 v[78:79], v[78:79], v[34:35] op_sel_hi:[1,0] neg_lo:[0,1] neg_hi:[0,1]
	v_pk_add_f32 v[62:63], v[62:63], v[34:35] op_sel_hi:[1,0] neg_lo:[0,1] neg_hi:[0,1]
	v_mov_b32_e32 v33, v32
	v_mov_b32_e32 v34, v32
	v_mov_b32_e32 v35, v32
	v_mov_b32_e32 v36, v32
	v_mov_b32_e32 v37, v32
	v_mov_b32_e32 v38, v32
	v_mov_b32_e32 v39, v32
	v_mov_b32_e32 v40, v32
	v_mov_b32_e32 v41, v32
	v_mov_b32_e32 v42, v32
	v_mov_b32_e32 v43, v32
	v_mov_b32_e32 v44, v32
	v_mov_b32_e32 v45, v32
	v_mov_b32_e32 v46, v32
	v_mov_b32_e32 v47, v32
	s_branch .LBB0_1418

; #define LAS __attribute__((address_space(3)))
; __device__ __forceinline__ bf16 f2bf(float f) { return (bf16)(pk2(f, 0.f) & 0xffffu); }
; __device__ __forceinline__ int crow(int r, int hi) { return (r & 3) + 8 * (r >> 2) + 4 * hi; }
; template <int VAR> __device__ __forceinline__ void block(const bf16* Q, const bf16* KVB, const bf16* KR, const float* cosT, bf16* OB, LAS unsigned char* lds, int b, int h, int qb, int t0, int wv, ...
;     ...
;     if (hi == 0) li_l[r32] = l_reg; asm volatile("s_waitcnt lgkmcnt(0)" ::: "memory");
;     bf16* Ow = OB + (rowbase + P0 + wid * 32) * DM + h * 64;
;     {
;         LAS bf16* stg = (LAS bf16*)(lds + LDS_OST) + wid * 2048;
; #pragma unroll
;         for (int r = 0; r < 16; ++r) { const int orow = crow(r, hi); const float rl = __builtin_amdgcn_rcpf(li_l[orow]);
; #pragma unroll
;             for (int d0 = 0; d0 < 2; ++d0) stg[orow * 64 + d0 * 32 + r32] = f2bf(o[d0][r] * rl); }
;         asm volatile("s_waitcnt lgkmcnt(0)" ::: "memory");
; #pragma unroll
;         for (int i4 = 0; i4 < 4; ++i4) { const int row = i4 * 8 + (lane >> 3), ch = lane & 7; const u32x4 v = *(const LAS u32x4*)(stg + row * 64 + ch * 8); *(u32x4*)(Ow + (size_t)row * DM + ch * 8) = v; }
;     }
.LBB0_1434:
	s_and_saveexec_b64 s[8:9], s[2:3]
	ds_write_b32 v171, v150
	s_or_b64 exec, exec, s[8:9]
	s_waitcnt lgkmcnt(0)
	ds_read_b128 v[32:35], v168
	ds_read_b128 v[36:39], v168 offset:32
	v_lshl_add_u32 v40, v161, 1, s97
	v_lshl_add_u32 v41, v162, 9, v40
	s_add_u32 s2, s72, s77
	s_waitcnt lgkmcnt(0)
	v_rcp_f32_e32 v32, v32
	s_addc_u32 s3, 0, s73
	s_lshl_b64 s[2:3], s[2:3], 11
	v_readlane_b32 s8, v254, 20
	v_mul_f32_e32 v16, v16, v32
	v_cvt_pk_bf16_f32 v16, v16, s0
	ds_write_b16 v41, v16
	v_rcp_f32_e32 v16, v33
	v_mul_f32_e32 v0, v0, v32
	v_cvt_pk_bf16_f32 v0, v0, s0
	ds_write_b16 v41, v0 offset:64
	v_mul_f32_e32 v0, v17, v16
	v_cvt_pk_bf16_f32 v0, v0, s0
	v_lshl_add_u32 v32, v166, 7, v40
	ds_write_b16 v32, v0 offset:128
	v_rcp_f32_e32 v0, v34
	v_mul_f32_e32 v1, v1, v16
	v_cvt_pk_bf16_f32 v1, v1, s0
	ds_write_b16 v32, v1 offset:192
	v_mul_f32_e32 v1, v18, v0
	v_cvt_pk_bf16_f32 v1, v1, s0
	ds_write_b16 v32, v1 offset:256
	v_rcp_f32_e32 v1, v35
	v_mul_f32_e32 v0, v2, v0
	v_cvt_pk_bf16_f32 v0, v0, s0
	ds_write_b16 v32, v0 offset:320
	v_mul_f32_e32 v0, v19, v1
	v_cvt_pk_bf16_f32 v0, v0, s0
	ds_write_b16 v32, v0 offset:384
	v_rcp_f32_e32 v0, v36
	v_mul_f32_e32 v1, v3, v1
	v_cvt_pk_bf16_f32 v1, v1, s0
	ds_write_b16 v32, v1 offset:448
	v_mul_f32_e32 v1, v20, v0
	v_cvt_pk_bf16_f32 v1, v1, s0
	ds_write_b16 v32, v1 offset:1024
	v_rcp_f32_e32 v1, v37
	v_mul_f32_e32 v0, v4, v0
	v_cvt_pk_bf16_f32 v0, v0, s0
	ds_write_b16 v32, v0 offset:1088
	v_mul_f32_e32 v0, v21, v1
	v_cvt_pk_bf16_f32 v0, v0, s0
	ds_write_b16 v32, v0 offset:1152
	v_rcp_f32_e32 v0, v38
	v_mul_f32_e32 v1, v5, v1
	v_cvt_pk_bf16_f32 v1, v1, s0
	ds_write_b16 v32, v1 offset:1216
	v_mul_f32_e32 v1, v22, v0
	v_mul_f32_e32 v0, v6, v0
	v_cvt_pk_bf16_f32 v1, v1, s0
	v_cvt_pk_bf16_f32 v0, v0, s0
	ds_write_b16 v32, v1 offset:1280
	ds_write_b16 v32, v0 offset:1344
	ds_read_b128 v[0:3], v168 offset:64
	ds_read_b128 v[16:19], v168 offset:96
	v_rcp_f32_e32 v4, v39
	s_add_u32 s2, s8, s2
	v_readlane_b32 s8, v254, 21
	s_waitcnt lgkmcnt(0)
	v_rcp_f32_e32 v0, v0
	v_mul_f32_e32 v5, v23, v4
	v_mul_f32_e32 v4, v7, v4
	v_rcp_f32_e32 v1, v1
	v_cvt_pk_bf16_f32 v4, v4, s0
	ds_write_b16 v32, v4 offset:1472
	v_mul_f32_e32 v4, v24, v0
	v_mul_f32_e32 v0, v8, v0
	v_cvt_pk_bf16_f32 v0, v0, s0
	ds_write_b16 v32, v0 offset:2112
	v_mul_f32_e32 v0, v25, v1
	v_cvt_pk_bf16_f32 v0, v0, s0
	ds_write_b16 v32, v0 offset:2176
	v_rcp_f32_e32 v0, v2
	v_mul_f32_e32 v1, v9, v1
	v_cvt_pk_bf16_f32 v1, v1, s0
	ds_write_b16 v32, v1 offset:2240
	v_mul_f32_e32 v1, v26, v0
	v_cvt_pk_bf16_f32 v1, v1, s0
	ds_write_b16 v32, v1 offset:2304
	v_rcp_f32_e32 v1, v3
	v_mul_f32_e32 v0, v10, v0
	v_cvt_pk_bf16_f32 v0, v0, s0
	ds_write_b16 v32, v0 offset:2368
	v_mul_f32_e32 v0, v27, v1
	v_cvt_pk_bf16_f32 v0, v0, s0
	ds_write_b16 v32, v0 offset:2432
	v_rcp_f32_e32 v0, v16
	v_mul_f32_e32 v1, v11, v1
	v_cvt_pk_bf16_f32 v1, v1, s0
	ds_write_b16 v32, v1 offset:2496
	v_mul_f32_e32 v1, v28, v0
	v_cvt_pk_bf16_f32 v1, v1, s0
	ds_write_b16 v32, v1 offset:3072
	v_rcp_f32_e32 v1, v17
	v_mul_f32_e32 v0, v12, v0
	v_cvt_pk_bf16_f32 v0, v0, s0
	ds_write_b16 v32, v0 offset:3136
	v_mul_f32_e32 v0, v29, v1
	v_cvt_pk_bf16_f32 v0, v0, s0
	ds_write_b16 v32, v0 offset:3200
	v_rcp_f32_e32 v0, v18
	v_mul_f32_e32 v1, v13, v1
	v_cvt_pk_bf16_f32 v1, v1, s0
	ds_write_b16 v32, v1 offset:3264
	v_mul_f32_e32 v1, v30, v0
	v_cvt_pk_bf16_f32 v1, v1, s0
	ds_write_b16 v32, v1 offset:3328
	v_rcp_f32_e32 v1, v19
	v_mul_f32_e32 v0, v14, v0
	v_cvt_pk_bf16_f32 v0, v0, s0
	ds_write_b16 v32, v0 offset:3392
	v_mul_f32_e32 v0, v31, v1
	v_cvt_pk_bf16_f32 v0, v0, s0
	ds_write_b16 v32, v0 offset:3456
	v_mul_f32_e32 v0, v15, v1
	v_cvt_pk_bf16_f32 v0, v0, s0
	ds_write_b16 v32, v0 offset:3520
	v_lshlrev_b32_e32 v0, 1, v160
	v_cvt_pk_bf16_f32 v5, v5, s0
	v_cvt_pk_bf16_f32 v4, v4, s0
	v_and_b32_e32 v152, 0x70, v0
	ds_write_b16 v32, v5 offset:1408
	ds_write_b16 v32, v4 offset:2048
	v_lshrrev_b32_e32 v12, 3, v167
	v_add_u32_e32 v13, s97, v152
	s_waitcnt lgkmcnt(0)
	v_lshl_add_u32 v0, v12, 7, v13
	v_or_b32_e32 v14, 8, v12
	s_addc_u32 s3, s8, s3
	s_lshl_b32 s8, s86, 1
	ds_read_b128 v[0:3], v0
	v_lshl_add_u32 v4, v14, 7, v13
	s_add_u32 s2, s2, s8
	ds_read_b128 v[4:7], v4
	s_addc_u32 s3, s3, 0
	v_lshl_add_u64 v[8:9], s[2:3], 0, v[152:153]
	v_lshlrev_b32_e32 v152, 11, v12
	v_lshl_add_u64 v[10:11], v[8:9], 0, v[152:153]
	v_lshlrev_b32_e32 v152, 11, v14
	s_waitcnt lgkmcnt(0)
	global_store_dwordx4 v[10:11], v[0:3], off
	s_andn2_b64 vcc, exec, s[4:5]
	s_nop 0
	v_lshl_add_u64 v[0:1], v[8:9], 0, v[152:153]
	global_store_dwordx4 v[0:1], v[4:7], off
	s_nop 1
	v_or_b32_e32 v4, 16, v12
	v_lshl_add_u32 v0, v4, 7, v13
	v_or_b32_e32 v12, 24, v12
	ds_read_b128 v[0:3], v0
	v_lshlrev_b32_e32 v152, 11, v4
	v_lshl_add_u32 v4, v12, 7, v13
	ds_read_b128 v[4:7], v4
	v_lshl_add_u64 v[10:11], v[8:9], 0, v[152:153]
	v_lshlrev_b32_e32 v152, 11, v12
	s_waitcnt lgkmcnt(0)
	global_store_dwordx4 v[10:11], v[0:3], off
	s_nop 1
	v_lshl_add_u64 v[0:1], v[8:9], 0, v[152:153]
	global_store_dwordx4 v[0:1], v[4:7], off
	s_cbranch_vccz .LBB0_1439
	s_andn2_b64 vcc, exec, s[6:7]
	s_mov_b32 s6, s76
	s_cbranch_vccz .LBB0_1440
